# PEER expert phase: s_setprio 3 on the per-XCD clock-leader wave (reset at phase end), on top of GEMM-phase priority
# speedup vs baseline: 1.0043x; 1.0043x over previous
.LBB0_598:
	s_barrier
	v_and_b32_e32 v249, 2, v60
	v_cmp_eq_u32_e64 s[6:7], 0, v249
	v_and_b32_e32 v249, 1, v60
	v_cmp_eq_u32_e64 s[0:1], 0, v249
	v_mov_b32_e32 v253, 0
	v_mov_b32_e32 v147, 0
	v_mov_b32_e32 v148, 0
	v_mov_b32_e32 v244, 0
	v_lshlrev_b32_e32 v248, 10, v58
	v_lshl_add_u32 v248, v60, 4, v248
	s_getreg_b32 s2, hwreg(HW_REG_XCC_ID)
	s_and_b32 s2, s2, 7
	s_lshl_b32 s2, s2, 7
	s_add_u32 s2, s2, s44
	s_addc_u32 s3, s45, 0
	s_add_u32 s2, s2, 0xffff8100
	s_addc_u32 s3, s3, -1
	v_mov_b32_e32 v246, s2
	v_mov_b32_e32 v247, s3
	v_mov_b32_e32 v250, 1
	s_mov_b64 exec, 1
	global_atomic_add v251, v[246:247], v250, off offset:1792 sc0
	s_mov_b64 exec, -1
	s_waitcnt vmcnt(0)
	v_readfirstlane_b32 s2, v251
	s_cmp_eq_u32 s2, 64
	s_cselect_b32 s82, 1, 0
	s_cmp_eq_u32 s82, 1
	s_cbranch_scc0 .Lxp_noprio
	s_setprio 3
.Lxp_noprio:
	s_and_b32 s79, s2, 1
	s_lshl_b32 s79, s79, 10
	s_lshr_b32 s78, s2, 1
	s_and_b32 s78, s78, 0x7f
	s_add_i32 s78, s78, 768
	s_mov_b32 s23, 0

.Lxp_end:
	s_setprio 0
	s_branch .LBB0_352

